# v39 + attention A/B loop-edge rotation (bookkeeping ahead of the barrier) + m0 save/restore removal around LDS-DMA
# speedup vs baseline: 1.0059x; 1.0022x over previous
.LBB0_383:
	v_add_u32_e32 v1, s20, v210
	ds_read_b64_tr_b16 v[178:179], v1 offset:24576
	ds_read_b64_tr_b16 v[180:181], v1 offset:25088
	s_waitcnt lgkmcnt(9)
	v_mfma_f32_32x32x16_bf16 v[98:113], v[174:177], v[130:133], v[34:49]
	v_add_f32_e32 v82, v66, v67
	v_add_f32_e32 v82, v68, v82
	v_add_f32_e32 v82, v69, v82
	v_add_f32_e32 v82, v70, v82
	v_add_f32_e32 v82, v71, v82
	v_cvt_pk_bf16_f32 v142, v66, v67
	v_cvt_pk_bf16_f32 v143, v68, v69
	ds_read_b64_tr_b16 v[174:175], v1 offset:28672
	ds_read_b64_tr_b16 v[176:177], v1 offset:29184
	v_add_f32_e32 v66, v72, v82
	s_waitcnt lgkmcnt(10)
	v_mfma_f32_32x32x16_bf16 v[82:97], v[170:173], v[130:133], v[34:49]
	v_add_f32_e32 v66, v73, v66
	v_add_f32_e32 v66, v74, v66
	v_add_f32_e32 v114, v75, v66
	v_cvt_pk_bf16_f32 v144, v70, v71
	v_cvt_pk_bf16_f32 v145, v72, v73
	ds_read_b64_tr_b16 v[66:67], v1 offset:25600
	ds_read_b64_tr_b16 v[68:69], v1 offset:26112
	s_waitcnt lgkmcnt(11)
	v_mfma_f32_32x32x16_bf16 v[98:113], v[166:169], v[122:125], v[98:113]
	v_add_f32_e32 v70, v76, v114
	v_add_f32_e32 v70, v77, v70
	v_add_f32_e32 v70, v78, v70
	v_add_f32_e32 v114, v79, v70
	v_cvt_pk_bf16_f32 v126, v74, v75
	v_cvt_pk_bf16_f32 v127, v76, v77
	ds_read_b64_tr_b16 v[70:71], v1 offset:29696
	ds_read_b64_tr_b16 v[72:73], v1 offset:30208
	s_waitcnt lgkmcnt(12)
	v_mfma_f32_32x32x16_bf16 v[82:97], v[162:165], v[122:125], v[82:97]
	v_add_f32_e32 v74, v80, v114
	v_add_f32_e32 v74, v81, v74
	v_add_f32_e32 v74, v50, v74
	v_add_f32_e32 v114, v51, v74
	v_cvt_pk_bf16_f32 v128, v78, v79
	v_cvt_pk_bf16_f32 v129, v80, v81
	ds_read_b64_tr_b16 v[74:75], v1 offset:26624
	ds_read_b64_tr_b16 v[76:77], v1 offset:27136
	s_waitcnt lgkmcnt(13)
	v_mfma_f32_32x32x16_bf16 v[98:113], v[158:161], v[138:141], v[98:113]
	v_add_f32_e32 v78, v52, v114
	v_add_f32_e32 v78, v53, v78
	v_add_f32_e32 v78, v54, v78
	v_add_f32_e32 v78, v55, v78
	v_cvt_pk_bf16_f32 v118, v50, v51
	v_cvt_pk_bf16_f32 v119, v52, v53
	ds_read_b64_tr_b16 v[50:51], v1 offset:30720
	ds_read_b64_tr_b16 v[52:53], v1 offset:31232
	s_waitcnt lgkmcnt(14)
	v_mfma_f32_32x32x16_bf16 v[82:97], v[154:157], v[138:141], v[82:97]
	v_add_f32_e32 v78, v56, v78
	v_add_f32_e32 v78, v57, v78
	v_add_f32_e32 v78, v58, v78
	v_add_f32_e32 v78, v59, v78
	v_cvt_pk_bf16_f32 v120, v54, v55
	v_cvt_pk_bf16_f32 v121, v56, v57
	ds_read_b64_tr_b16 v[54:55], v1 offset:27648
	ds_read_b64_tr_b16 v[56:57], v1 offset:28160
	s_waitcnt lgkmcnt(14)
	v_mfma_f32_32x32x16_bf16 v[98:113], v[150:153], v[134:137], v[98:113]
	v_add_f32_e32 v78, v60, v78
	v_add_f32_e32 v78, v61, v78
	v_add_f32_e32 v78, v62, v78
	v_add_f32_e32 v78, v63, v78
	v_cvt_pk_bf16_f32 v114, v58, v59
	v_cvt_pk_bf16_f32 v115, v60, v61
	ds_read_b64_tr_b16 v[58:59], v1 offset:31744
	ds_read_b64_tr_b16 v[60:61], v1 offset:32256
	v_mfma_f32_32x32x16_bf16 v[82:97], v[146:149], v[134:137], v[82:97]
	v_add_f32_e32 v1, v64, v78
	v_add_f32_e32 v1, v65, v1
	v_cvt_pk_bf16_f32 v116, v62, v63
	v_cvt_pk_bf16_f32 v117, v64, v65
	s_add_i32 s2, s3, s22
	s_mov_b32 m0, s2
	s_nop 0
	global_load_lds_dwordx4 v213, s[98:99]
	s_add_i32 s2, s27, s23
	s_mov_b32 m0, s2
	s_nop 0
	global_load_lds_dwordx4 v215, s[98:99]
	v_max_f32_e32 v62, v98, v99
	v_max3_f32 v63, v100, v101, v83
	v_max3_f32 v62, v62, v82, v84
	v_max3_f32 v62, v62, v85, v102
	v_max3_f32 v63, v63, v104, v105
	v_max3_f32 v62, v62, v103, v86
	v_max3_f32 v63, v63, v88, v89
	v_max3_f32 v62, v62, v87, v106
	v_max3_f32 v63, v63, v108, v109
	v_max3_f32 v62, v62, v107, v90
	v_max3_f32 v63, v63, v92, v93
	v_max3_f32 v62, v62, v91, v110
	v_max3_f32 v63, v63, v112, v113
	v_max3_f32 v62, v62, v111, v94
	v_max3_f32 v63, v63, v96, v97
	v_max3_f32 v62, v62, v95, v63
	v_cmp_lt_f32_e32 vcc, s19, v62
	s_cmp_lg_u64 vcc, 0
	v_add_f32_e32 v1, v212, v1
	s_cselect_b64 s[6:7], -1, 0
	s_cbranch_vccnz .LBB0_391
.LBB0_384:
	s_waitcnt lgkmcnt(14)
	v_mfma_f32_32x32x16_bf16 v[2:17], v[142:145], v[178:181], v[2:17]
	v_exp_f32_e32 v98, v98
	v_exp_f32_e32 v99, v99
	v_exp_f32_e32 v100, v100
	v_exp_f32_e32 v101, v101
	s_waitcnt lgkmcnt(12)
	v_mfma_f32_32x32x16_bf16 v[18:33], v[142:145], v[174:177], v[18:33]
	v_exp_f32_e32 v102, v102
	v_exp_f32_e32 v103, v103
	v_exp_f32_e32 v104, v104
	v_exp_f32_e32 v105, v105
	v_add_u32_e32 v78, s27, v211
	ds_read_b128 v[62:65], v78
	ds_read_b128 v[174:177], v78 offset:512
	s_waitcnt lgkmcnt(12)
	v_mfma_f32_32x32x16_bf16 v[2:17], v[126:129], v[66:69], v[2:17]
	v_exp_f32_e32 v106, v106
	v_exp_f32_e32 v107, v107
	v_exp_f32_e32 v108, v108
	v_exp_f32_e32 v109, v109
	ds_read_b128 v[178:181], v78 offset:2048
	ds_read_b128 v[170:173], v78 offset:2560
	s_waitcnt lgkmcnt(12)
	v_mfma_f32_32x32x16_bf16 v[18:33], v[126:129], v[70:73], v[18:33]
	v_exp_f32_e32 v110, v110
	v_exp_f32_e32 v111, v111
	v_exp_f32_e32 v112, v112
	v_exp_f32_e32 v113, v113
	ds_read_b128 v[166:169], v78 offset:4096
	ds_read_b128 v[162:165], v78 offset:4608
	s_waitcnt lgkmcnt(12)
	v_mfma_f32_32x32x16_bf16 v[2:17], v[118:121], v[74:77], v[2:17]
	v_exp_f32_e32 v82, v82
	v_exp_f32_e32 v83, v83
	v_exp_f32_e32 v84, v84
	v_exp_f32_e32 v85, v85
	ds_read_b128 v[158:161], v78 offset:6144
	ds_read_b128 v[154:157], v78 offset:6656
	s_waitcnt lgkmcnt(12)
	v_mfma_f32_32x32x16_bf16 v[18:33], v[118:121], v[50:53], v[18:33]
	v_exp_f32_e32 v86, v86
	v_exp_f32_e32 v87, v87
	v_exp_f32_e32 v88, v88
	v_exp_f32_e32 v89, v89
	s_waitcnt lgkmcnt(10)
	v_mfma_f32_32x32x16_bf16 v[2:17], v[114:117], v[54:57], v[2:17]
	v_exp_f32_e32 v90, v90
	v_exp_f32_e32 v91, v91
	v_exp_f32_e32 v92, v92
	v_exp_f32_e32 v93, v93
	s_waitcnt lgkmcnt(8)
	v_mfma_f32_32x32x16_bf16 v[18:33], v[114:117], v[58:61], v[18:33]
	v_exp_f32_e32 v94, v94
	v_exp_f32_e32 v95, v95
	v_exp_f32_e32 v96, v96
	v_exp_f32_e32 v97, v97
	s_add_i32 s2, s27, 0x2000
	s_cmpk_lg_i32 s27, 0x4000
	s_cselect_b32 s14, s2, 0
	s_waitcnt vmcnt(2) lgkmcnt(0)
	s_barrier
	s_andn2_b64 vcc, exec, s[6:7]
	s_cbranch_vccnz .LBB0_386
	s_waitcnt lgkmcnt(0)
	v_add_u32_e32 v66, s25, v193
	ds_read_b128 v[50:53], v66 offset:96
	ds_read_b128 v[54:57], v66 offset:64
	ds_read_b128 v[58:61], v66 offset:32
	ds_read_b128 v[66:69], v66
	s_waitcnt lgkmcnt(3)
	v_pk_mul_f32 v[14:15], v[14:15], v[50:51]
	s_waitcnt lgkmcnt(2)
	v_pk_mul_f32 v[10:11], v[10:11], v[54:55]
	s_waitcnt lgkmcnt(1)
	v_pk_mul_f32 v[6:7], v[6:7], v[58:59]
	v_pk_mul_f32 v[16:17], v[16:17], v[52:53]
	v_pk_mul_f32 v[12:13], v[12:13], v[56:57]
	v_pk_mul_f32 v[8:9], v[8:9], v[60:61]
	s_waitcnt lgkmcnt(0)
	v_pk_mul_f32 v[4:5], v[4:5], v[68:69]
	v_pk_mul_f32 v[2:3], v[2:3], v[66:67]
	v_pk_mul_f32 v[30:31], v[30:31], v[50:51]
	v_pk_mul_f32 v[26:27], v[26:27], v[54:55]
	v_pk_mul_f32 v[22:23], v[22:23], v[58:59]
	v_pk_mul_f32 v[32:33], v[32:33], v[52:53]
	v_pk_mul_f32 v[28:29], v[28:29], v[56:57]
	v_pk_mul_f32 v[24:25], v[24:25], v[60:61]
	v_pk_mul_f32 v[20:21], v[20:21], v[68:69]
	v_pk_mul_f32 v[18:19], v[18:19], v[66:67]
.LBB0_386:
	v_add_u32_e32 v186, s3, v210
	ds_read_b64_tr_b16 v[150:151], v186 offset:24576
	ds_read_b64_tr_b16 v[152:153], v186 offset:25088
	s_waitcnt lgkmcnt(9)
	v_mfma_f32_32x32x16_bf16 v[66:81], v[62:65], v[130:133], v[34:49]
	v_add_f32_e32 v50, v98, v99
	v_add_f32_e32 v50, v100, v50
	v_add_f32_e32 v50, v101, v50
	v_add_f32_e32 v50, v102, v50
	v_add_f32_e32 v50, v103, v50
	v_cvt_pk_bf16_f32 v142, v98, v99
	v_cvt_pk_bf16_f32 v143, v100, v101
	ds_read_b64_tr_b16 v[146:147], v186 offset:28672
	ds_read_b64_tr_b16 v[148:149], v186 offset:29184
	v_add_f32_e32 v50, v104, v50
	v_add_f32_e32 v50, v105, v50
	v_add_f32_e32 v50, v106, v50
	v_add_f32_e32 v114, v107, v50
	s_waitcnt lgkmcnt(10)
	v_mfma_f32_32x32x16_bf16 v[50:65], v[174:177], v[130:133], v[34:49]
	v_cvt_pk_bf16_f32 v144, v102, v103
	v_cvt_pk_bf16_f32 v145, v104, v105
	ds_read_b64_tr_b16 v[98:99], v186 offset:25600
	ds_read_b64_tr_b16 v[100:101], v186 offset:26112
	s_waitcnt lgkmcnt(11)
	v_mfma_f32_32x32x16_bf16 v[66:81], v[178:181], v[122:125], v[66:81]
	v_add_f32_e32 v102, v108, v114
	v_add_f32_e32 v102, v109, v102
	v_add_f32_e32 v102, v110, v102
	v_add_f32_e32 v114, v111, v102
	v_cvt_pk_bf16_f32 v126, v106, v107
	v_cvt_pk_bf16_f32 v127, v108, v109
	ds_read_b64_tr_b16 v[102:103], v186 offset:29696
	ds_read_b64_tr_b16 v[104:105], v186 offset:30208
	s_waitcnt lgkmcnt(12)
	v_mfma_f32_32x32x16_bf16 v[50:65], v[170:173], v[122:125], v[50:65]
	v_add_f32_e32 v106, v112, v114
	v_add_f32_e32 v106, v113, v106
	v_add_f32_e32 v106, v82, v106
	v_add_f32_e32 v114, v83, v106
	v_cvt_pk_bf16_f32 v128, v110, v111
	v_cvt_pk_bf16_f32 v129, v112, v113
	ds_read_b64_tr_b16 v[106:107], v186 offset:26624
	ds_read_b64_tr_b16 v[108:109], v186 offset:27136
	s_waitcnt lgkmcnt(13)
	v_mfma_f32_32x32x16_bf16 v[66:81], v[166:169], v[138:141], v[66:81]
	v_add_f32_e32 v110, v84, v114
	v_add_f32_e32 v110, v85, v110
	v_add_f32_e32 v110, v86, v110
	v_add_f32_e32 v110, v87, v110
	v_cvt_pk_bf16_f32 v118, v82, v83
	v_cvt_pk_bf16_f32 v119, v84, v85
	ds_read_b64_tr_b16 v[82:83], v186 offset:30720
	ds_read_b64_tr_b16 v[84:85], v186 offset:31232
	s_waitcnt lgkmcnt(14)
	v_mfma_f32_32x32x16_bf16 v[50:65], v[162:165], v[138:141], v[50:65]
	v_add_f32_e32 v110, v88, v110
	v_add_f32_e32 v110, v89, v110
	v_add_f32_e32 v110, v90, v110
	v_add_f32_e32 v110, v91, v110
	v_cvt_pk_bf16_f32 v120, v86, v87
	v_cvt_pk_bf16_f32 v121, v88, v89
	ds_read_b64_tr_b16 v[86:87], v186 offset:27648
	ds_read_b64_tr_b16 v[88:89], v186 offset:28160
	s_waitcnt lgkmcnt(14)
	v_mfma_f32_32x32x16_bf16 v[66:81], v[158:161], v[134:137], v[66:81]
	v_add_f32_e32 v110, v92, v110
	v_add_f32_e32 v110, v93, v110
	v_add_f32_e32 v110, v94, v110
	v_add_f32_e32 v110, v95, v110
	v_cvt_pk_bf16_f32 v114, v90, v91
	v_cvt_pk_bf16_f32 v115, v92, v93
	ds_read_b64_tr_b16 v[90:91], v186 offset:31744
	ds_read_b64_tr_b16 v[92:93], v186 offset:32256
	v_mfma_f32_32x32x16_bf16 v[50:65], v[154:157], v[134:137], v[50:65]
	v_add_f32_e32 v110, v96, v110
	v_add_f32_e32 v110, v97, v110
	v_cvt_pk_bf16_f32 v116, v94, v95
	v_cvt_pk_bf16_f32 v117, v96, v97
	v_max_f32_e32 v94, v66, v67
	v_max3_f32 v95, v68, v69, v70
	v_max3_f32 v94, v94, v71, v72
	v_max3_f32 v95, v95, v73, v74
	v_max3_f32 v94, v94, v75, v76
	v_max3_f32 v95, v95, v77, v78
	v_max3_f32 v94, v94, v79, v80
	v_add_f32_e32 v212, v1, v110
	v_max3_f32 v95, v95, v81, v50
	v_max3_f32 v94, v94, v51, v52
	v_max3_f32 v95, v95, v53, v54
	v_max3_f32 v94, v94, v55, v56
	v_max3_f32 v95, v95, v57, v58
	v_max3_f32 v94, v94, v59, v60
	v_max3_f32 v95, v95, v61, v62
	v_max3_f32 v94, v94, v63, v64
	v_max3_f32 v1, v94, v65, v95
	s_add_i32 s2, s27, s22
	s_mov_b32 m0, s2
	s_nop 0
	global_load_lds_dwordx4 v214, s[98:99]
	s_add_i32 s2, s14, s23
	s_mov_b32 m0, s2
	s_nop 0
	global_load_lds_dwordx4 v216, s[98:99]
	v_cmp_lt_f32_e32 vcc, s19, v1
	s_cmp_lg_u64 vcc, 0
	s_cselect_b64 s[6:7], -1, 0
	s_cbranch_vccnz .LBB0_394

;   #define WAIT_KV() do{ if constexpr(DV==128){WAIT_BAR(3);} else {WAIT_BAR(2);} }while(0)
;   #define RESC() do{ if(resc){ asm volatile("s_waitcnt lgkmcnt(0)":::"memory"); \
;       _Pragma("unroll") for(int d_=0;d_<DV/32;++d_) _Pragma("unroll") for(int r=0;r<16;++r)o[d_][r]*=wsf[crow(r,hi)]; } }while(0)
;   #define ROT() do{sl_prev=sl_cur;sl_cur=sl_next;sl_next=(sl_next==(NSLOT-1)*SLOTB)?0:sl_next+SLOTB;}while(0)
; template<int THRL,bool WIN,int DM,int ODM,int DV,int QMODE> __device__ __forceinline__ void attn_unit(const bf16*Qp,const bf16*__restrict__ Kp,const bf16*__restrict__ Vp,bf16*Op,const int q0,const int t_lo,const int NT,const float sink2,char*shm,const float*qgain,const float*qtab,const int b0,const ...
;     ...
;   int t=1;
;   for(;t+5<NT;t+=2){
;     STEP(pB0,pB1,pA0,pA1,t,true,true,true);     WAIT_KV(); RESC(); ROT();
;     STEP(pA0,pA1,pB0,pB1,t+1,true,true,true);   WAIT_KV(); RESC(); ROT();
;   }
.LBB0_389:
	s_add_i32 s13, s13, 2
	s_add_i32 s2, s14, 0x2000
	s_cmpk_lg_i32 s14, 0x4000
	s_cselect_b32 s2, s2, 0
	s_add_i32 s3, s26, 2
	s_add_u32 s98, s98, 0x90000
	s_addc_u32 s99, s99, 0
	s_add_u32 s100, s100, 0x90000
	s_addc_u32 s101, s101, 0
	s_cmp_ge_u32 s13, s15
	s_cbranch_scc1 .Lmy_a_exitbar
	s_mov_b32 s26, s3
	s_mov_b32 s20, s27
	s_mov_b32 s3, s14
	s_mov_b32 s27, s2
	s_waitcnt vmcnt(2) lgkmcnt(0)
	s_barrier
	s_andn2_b64 vcc, exec, s[6:7]
	s_cbranch_vccnz .LBB0_383
	s_waitcnt lgkmcnt(0)
	v_add_u32_e32 v1, s25, v193
	ds_read_b128 v[82:85], v1 offset:96
	ds_read_b128 v[86:89], v1 offset:64
	ds_read_b128 v[90:93], v1 offset:32
	ds_read_b128 v[94:97], v1
	s_waitcnt lgkmcnt(3)
	v_pk_mul_f32 v[14:15], v[14:15], v[82:83]
	s_waitcnt lgkmcnt(2)
	v_pk_mul_f32 v[10:11], v[10:11], v[86:87]
	s_waitcnt lgkmcnt(1)
	v_pk_mul_f32 v[6:7], v[6:7], v[90:91]
	v_pk_mul_f32 v[16:17], v[16:17], v[84:85]
	v_pk_mul_f32 v[12:13], v[12:13], v[88:89]
	v_pk_mul_f32 v[8:9], v[8:9], v[92:93]
	s_waitcnt lgkmcnt(0)
	v_pk_mul_f32 v[4:5], v[4:5], v[96:97]
	v_pk_mul_f32 v[2:3], v[2:3], v[94:95]
	v_pk_mul_f32 v[30:31], v[30:31], v[82:83]
	v_pk_mul_f32 v[26:27], v[26:27], v[86:87]
	v_pk_mul_f32 v[22:23], v[22:23], v[90:91]
	v_pk_mul_f32 v[32:33], v[32:33], v[84:85]
	v_pk_mul_f32 v[28:29], v[28:29], v[88:89]
	v_pk_mul_f32 v[24:25], v[24:25], v[92:93]
	v_pk_mul_f32 v[20:21], v[20:21], v[96:97]
	v_pk_mul_f32 v[18:19], v[18:19], v[94:95]
	s_branch .LBB0_383
.Lmy_a_exitbar:
	s_waitcnt vmcnt(2) lgkmcnt(0)
	s_barrier
	s_andn2_b64 vcc, exec, s[6:7]
	s_cbranch_vccnz .Lmy_a_exit
	s_waitcnt lgkmcnt(0)
	v_add_u32_e32 v1, s25, v193
	ds_read_b128 v[82:85], v1 offset:96
	ds_read_b128 v[86:89], v1 offset:64
	ds_read_b128 v[90:93], v1 offset:32
	ds_read_b128 v[94:97], v1
	s_waitcnt lgkmcnt(3)
	v_pk_mul_f32 v[14:15], v[14:15], v[82:83]
	s_waitcnt lgkmcnt(2)
	v_pk_mul_f32 v[10:11], v[10:11], v[86:87]
	s_waitcnt lgkmcnt(1)
	v_pk_mul_f32 v[6:7], v[6:7], v[90:91]
	v_pk_mul_f32 v[16:17], v[16:17], v[84:85]
	v_pk_mul_f32 v[12:13], v[12:13], v[88:89]
	v_pk_mul_f32 v[8:9], v[8:9], v[92:93]
	s_waitcnt lgkmcnt(0)
	v_pk_mul_f32 v[4:5], v[4:5], v[96:97]
	v_pk_mul_f32 v[2:3], v[2:3], v[94:95]
	v_pk_mul_f32 v[30:31], v[30:31], v[82:83]
	v_pk_mul_f32 v[26:27], v[26:27], v[86:87]
	v_pk_mul_f32 v[22:23], v[22:23], v[90:91]
	v_pk_mul_f32 v[32:33], v[32:33], v[84:85]
	v_pk_mul_f32 v[28:29], v[28:29], v[88:89]
	v_pk_mul_f32 v[24:25], v[24:25], v[92:93]
	v_pk_mul_f32 v[20:21], v[20:21], v[96:97]
	v_pk_mul_f32 v[18:19], v[18:19], v[94:95]

.LBB0_465:
	s_lshl_b32 s2, s15, 1
	v_add_u32_e32 v216, s2, v249
	ds_read_b64_tr_b16 v[210:211], v216 offset:24576
	ds_read_b64_tr_b16 v[212:213], v216 offset:25088
	s_waitcnt lgkmcnt(9)
	v_mfma_f32_32x32x16_bf16 v[130:145], v[206:209], v[174:177], v[66:81]
	v_add_f32_e32 v1, v98, v99
	v_add_f32_e32 v1, v100, v1
	v_add_f32_e32 v1, v101, v1
	v_add_f32_e32 v1, v102, v1
	v_add_f32_e32 v1, v103, v1
	v_cvt_pk_bf16_f32 v158, v98, v99
	v_cvt_pk_bf16_f32 v159, v100, v101
	ds_read_b64_tr_b16 v[98:99], v216 offset:28672
	ds_read_b64_tr_b16 v[100:101], v216 offset:29184
	s_waitcnt lgkmcnt(10)
	v_mfma_f32_32x32x16_bf16 v[114:129], v[202:205], v[174:177], v[66:81]
	v_add_f32_e32 v1, v104, v1
	v_add_f32_e32 v1, v105, v1
	v_add_f32_e32 v1, v106, v1
	v_add_f32_e32 v1, v107, v1
	v_cvt_pk_bf16_f32 v160, v102, v103
	v_cvt_pk_bf16_f32 v161, v104, v105
	ds_read_b64_tr_b16 v[102:103], v216 offset:25600
	ds_read_b64_tr_b16 v[104:105], v216 offset:26112
	s_waitcnt lgkmcnt(11)
	v_mfma_f32_32x32x16_bf16 v[130:145], v[198:201], v[162:165], v[130:145]
	v_add_f32_e32 v1, v108, v1
	v_add_f32_e32 v1, v109, v1
	v_add_f32_e32 v1, v110, v1
	v_add_f32_e32 v1, v111, v1
	v_cvt_pk_bf16_f32 v154, v106, v107
	v_cvt_pk_bf16_f32 v155, v108, v109
	ds_read_b64_tr_b16 v[106:107], v216 offset:29696
	ds_read_b64_tr_b16 v[108:109], v216 offset:30208
	s_waitcnt lgkmcnt(12)
	v_mfma_f32_32x32x16_bf16 v[114:129], v[194:197], v[162:165], v[114:129]
	v_add_f32_e32 v1, v112, v1
	v_add_f32_e32 v1, v113, v1
	v_add_f32_e32 v1, v82, v1
	v_add_f32_e32 v1, v83, v1
	v_cvt_pk_bf16_f32 v156, v110, v111
	v_cvt_pk_bf16_f32 v157, v112, v113
	ds_read_b64_tr_b16 v[110:111], v216 offset:26624
	ds_read_b64_tr_b16 v[112:113], v216 offset:27136
	s_waitcnt lgkmcnt(13)
	v_mfma_f32_32x32x16_bf16 v[130:145], v[190:193], v[170:173], v[130:145]
	v_add_f32_e32 v1, v84, v1
	v_add_f32_e32 v1, v85, v1
	v_add_f32_e32 v1, v86, v1
	v_add_f32_e32 v1, v87, v1
	v_cvt_pk_bf16_f32 v150, v82, v83
	v_cvt_pk_bf16_f32 v151, v84, v85
	ds_read_b64_tr_b16 v[82:83], v216 offset:30720
	ds_read_b64_tr_b16 v[84:85], v216 offset:31232
	s_waitcnt lgkmcnt(14)
	v_mfma_f32_32x32x16_bf16 v[114:129], v[186:189], v[170:173], v[114:129]
	v_add_f32_e32 v1, v88, v1
	v_add_f32_e32 v1, v89, v1
	v_add_f32_e32 v1, v90, v1
	v_add_f32_e32 v1, v91, v1
	v_cvt_pk_bf16_f32 v152, v86, v87
	v_cvt_pk_bf16_f32 v153, v88, v89
	ds_read_b64_tr_b16 v[86:87], v216 offset:27648
	ds_read_b64_tr_b16 v[88:89], v216 offset:28160
	s_waitcnt lgkmcnt(14)
	v_mfma_f32_32x32x16_bf16 v[130:145], v[182:185], v[166:169], v[130:145]
	v_add_f32_e32 v1, v92, v1
	v_add_f32_e32 v1, v93, v1
	v_add_f32_e32 v1, v94, v1
	v_add_f32_e32 v1, v95, v1
	v_cvt_pk_bf16_f32 v146, v90, v91
	v_cvt_pk_bf16_f32 v147, v92, v93
	ds_read_b64_tr_b16 v[90:91], v216 offset:31744
	ds_read_b64_tr_b16 v[92:93], v216 offset:32256
	v_mfma_f32_32x32x16_bf16 v[114:129], v[178:181], v[166:169], v[114:129]
	v_add_f32_e32 v1, v96, v1
	v_add_f32_e32 v1, v97, v1
	v_cvt_pk_bf16_f32 v148, v94, v95
	v_cvt_pk_bf16_f32 v149, v96, v97
	s_add_i32 s2, s3, s47
	s_mov_b32 m0, s2
	s_nop 0
	global_load_lds_dwordx4 v234, s[98:99]
	s_lshl_b32 s51, s36, 1
	s_add_i32 s2, s51, s64
	s_mov_b32 m0, s2
	s_nop 0
	global_load_lds_dwordx4 v236, s[98:99]
	s_addk_i32 s2, 0x2000
	s_mov_b32 m0, s2
	s_nop 0
	global_load_lds_dwordx4 v238, s[98:99]
	v_max_f32_e32 v94, v130, v131
	v_max3_f32 v95, v132, v133, v115
	v_max3_f32 v94, v94, v114, v116
	v_max3_f32 v94, v94, v117, v134
	v_max3_f32 v95, v95, v136, v137
	v_max3_f32 v94, v94, v135, v118
	v_max3_f32 v95, v95, v120, v121
	v_max3_f32 v94, v94, v119, v138
	v_max3_f32 v95, v95, v140, v141
	v_max3_f32 v94, v94, v139, v122
	v_max3_f32 v95, v95, v124, v125
	v_max3_f32 v94, v94, v123, v142
	v_max3_f32 v95, v95, v144, v145
	v_max3_f32 v94, v94, v143, v126
	v_max3_f32 v95, v95, v128, v129
	v_max3_f32 v94, v94, v127, v95
	v_cmp_lt_f32_e32 vcc, s19, v94
	s_cmp_lg_u64 vcc, 0
	v_add_f32_e32 v1, v215, v1
	s_cselect_b64 s[92:93], -1, 0
	s_cbranch_vccnz .LBB0_473
.LBB0_466:
	s_waitcnt lgkmcnt(14)
	v_mfma_f32_32x32x16_bf16 v[50:65], v[158:161], v[210:213], v[50:65]
	v_exp_f32_e32 v130, v130
	v_exp_f32_e32 v131, v131
	ds_read_b64_tr_b16 v[94:95], v216 offset:32768
	ds_read_b64_tr_b16 v[96:97], v216 offset:33280
	s_waitcnt lgkmcnt(14)
	v_mfma_f32_32x32x16_bf16 v[34:49], v[158:161], v[98:101], v[34:49]
	v_exp_f32_e32 v132, v132
	v_exp_f32_e32 v133, v133
	ds_read_b64_tr_b16 v[98:99], v216 offset:36864
	ds_read_b64_tr_b16 v[100:101], v216 offset:37376
	s_waitcnt lgkmcnt(14)
	v_mfma_f32_32x32x16_bf16 v[50:65], v[154:157], v[102:105], v[50:65]
	v_exp_f32_e32 v134, v134
	v_exp_f32_e32 v135, v135
	ds_read_b64_tr_b16 v[102:103], v216 offset:33792
	ds_read_b64_tr_b16 v[104:105], v216 offset:34304
	s_waitcnt lgkmcnt(14)
	v_mfma_f32_32x32x16_bf16 v[34:49], v[154:157], v[106:109], v[34:49]
	v_exp_f32_e32 v136, v136
	v_exp_f32_e32 v137, v137
	ds_read_b64_tr_b16 v[106:107], v216 offset:37888
	ds_read_b64_tr_b16 v[108:109], v216 offset:38400
	s_waitcnt lgkmcnt(14)
	v_mfma_f32_32x32x16_bf16 v[50:65], v[150:153], v[110:113], v[50:65]
	v_exp_f32_e32 v138, v138
	v_exp_f32_e32 v139, v139
	ds_read_b64_tr_b16 v[110:111], v216 offset:34816
	ds_read_b64_tr_b16 v[112:113], v216 offset:35328
	s_waitcnt lgkmcnt(14)
	v_mfma_f32_32x32x16_bf16 v[34:49], v[150:153], v[82:85], v[34:49]
	v_exp_f32_e32 v140, v140
	v_exp_f32_e32 v141, v141
	ds_read_b64_tr_b16 v[190:191], v216 offset:38912
	ds_read_b64_tr_b16 v[192:193], v216 offset:39424
	s_waitcnt lgkmcnt(14)
	v_mfma_f32_32x32x16_bf16 v[50:65], v[146:149], v[86:89], v[50:65]
	v_exp_f32_e32 v142, v142
	v_exp_f32_e32 v143, v143
	ds_read_b64_tr_b16 v[86:87], v216 offset:35840
	ds_read_b64_tr_b16 v[88:89], v216 offset:36352
	s_waitcnt lgkmcnt(14)
;   #define WAIT_KV() do{ if constexpr(DV==128){WAIT_BAR(3);} else {WAIT_BAR(2);} }while(0)
;   #define RESC() do{ if(resc){ asm volatile("s_waitcnt lgkmcnt(0)":::"memory"); \
;       _Pragma("unroll") for(int d_=0;d_<DV/32;++d_) _Pragma("unroll") for(int r=0;r<16;++r)o[d_][r]*=wsf[crow(r,hi)]; } }while(0)
;   #define ROT() do{sl_prev=sl_cur;sl_cur=sl_next;sl_next=(sl_next==(NSLOT-1)*SLOTB)?0:sl_next+SLOTB;}while(0)
; template<int THRL,bool WIN,int DM,int ODM,int DV,int QMODE> __device__ __forceinline__ void attn_unit(const bf16*Qp,const bf16*__restrict__ Kp,const bf16*__restrict__ Vp,bf16*Op,const int q0,const int t_lo,const int NT,const float sink2,char*shm,const float*qgain,const float*qtab,const int b0,const ...
;     ...
;   int t=1;
;   for(;t+5<NT;t+=2){
;     STEP(pB0,pB1,pA0,pA1,t,true,true,true);     WAIT_KV(); RESC(); ROT();
;     STEP(pA0,pA1,pB0,pB1,t+1,true,true,true);   WAIT_KV(); RESC(); ROT();
	v_mfma_f32_32x32x16_bf16 v[34:49], v[146:149], v[90:93], v[34:49]
	v_exp_f32_e32 v144, v144
	v_exp_f32_e32 v145, v145
	ds_read_b64_tr_b16 v[90:91], v216 offset:39936
	ds_read_b64_tr_b16 v[92:93], v216 offset:40448
	s_waitcnt lgkmcnt(14)
	v_mfma_f32_32x32x16_bf16 v[18:33], v[158:161], v[94:97], v[18:33]
	v_exp_f32_e32 v114, v114
	v_exp_f32_e32 v115, v115
	s_waitcnt lgkmcnt(12)
	v_mfma_f32_32x32x16_bf16 v[2:17], v[158:161], v[98:101], v[2:17]
	v_exp_f32_e32 v116, v116
	v_exp_f32_e32 v117, v117
	v_add_u32_e32 v94, s36, v214
	ds_read_b128 v[82:85], v94
	ds_read_b128 v[202:205], v94 offset:512
	s_waitcnt lgkmcnt(12)
	v_mfma_f32_32x32x16_bf16 v[18:33], v[154:157], v[102:105], v[18:33]
	v_exp_f32_e32 v118, v118
	v_exp_f32_e32 v119, v119
	ds_read_b128 v[206:209], v94 offset:2048
	ds_read_b128 v[198:201], v94 offset:2560
	s_waitcnt lgkmcnt(12)
	v_mfma_f32_32x32x16_bf16 v[2:17], v[154:157], v[106:109], v[2:17]
	v_exp_f32_e32 v120, v120
	v_exp_f32_e32 v121, v121
	ds_read_b128 v[194:197], v94 offset:4096
	ds_read_b128 v[186:189], v94 offset:4608
	s_waitcnt lgkmcnt(12)
	v_mfma_f32_32x32x16_bf16 v[18:33], v[150:153], v[110:113], v[18:33]
	v_exp_f32_e32 v122, v122
	v_exp_f32_e32 v123, v123
	ds_read_b128 v[182:185], v94 offset:6144
	ds_read_b128 v[178:181], v94 offset:6656
	s_waitcnt lgkmcnt(12)
	v_mfma_f32_32x32x16_bf16 v[2:17], v[150:153], v[190:193], v[2:17]
	v_exp_f32_e32 v124, v124
	v_exp_f32_e32 v125, v125
	s_waitcnt lgkmcnt(10)
	v_mfma_f32_32x32x16_bf16 v[18:33], v[146:149], v[86:89], v[18:33]
	v_exp_f32_e32 v126, v126
	v_exp_f32_e32 v127, v127
	s_waitcnt lgkmcnt(8)
	v_mfma_f32_32x32x16_bf16 v[2:17], v[146:149], v[90:93], v[2:17]
	v_exp_f32_e32 v128, v128
	v_exp_f32_e32 v129, v129
	s_add_i32 s2, s36, 0x2000
	s_cmpk_lg_i32 s36, 0x4000
	s_cselect_b32 s14, s2, 0
	s_lshl_b32 s2, s3, 1
	s_waitcnt vmcnt(3) lgkmcnt(0)
	s_barrier
	s_andn2_b64 vcc, exec, s[92:93]
	s_cbranch_vccnz .LBB0_468
	s_waitcnt lgkmcnt(0)
	v_add_u32_e32 v98, s65, v243
	ds_read_b128 v[86:89], v98 offset:96
	ds_read_b128 v[90:93], v98 offset:64
	ds_read_b128 v[94:97], v98 offset:32
	ds_read_b128 v[98:101], v98
	s_waitcnt lgkmcnt(3)
	v_pk_mul_f32 v[62:63], v[62:63], v[86:87]
	s_waitcnt lgkmcnt(2)
	v_pk_mul_f32 v[58:59], v[58:59], v[90:91]
	s_waitcnt lgkmcnt(1)
	v_pk_mul_f32 v[54:55], v[54:55], v[94:95]
	v_pk_mul_f32 v[64:65], v[64:65], v[88:89]
	v_pk_mul_f32 v[60:61], v[60:61], v[92:93]
	v_pk_mul_f32 v[56:57], v[56:57], v[96:97]
	s_waitcnt lgkmcnt(0)
	v_pk_mul_f32 v[52:53], v[52:53], v[100:101]
	v_pk_mul_f32 v[50:51], v[50:51], v[98:99]
	v_pk_mul_f32 v[46:47], v[46:47], v[86:87]
	v_pk_mul_f32 v[42:43], v[42:43], v[90:91]
	v_pk_mul_f32 v[38:39], v[38:39], v[94:95]
	v_pk_mul_f32 v[48:49], v[48:49], v[88:89]
	v_pk_mul_f32 v[44:45], v[44:45], v[92:93]
	v_pk_mul_f32 v[40:41], v[40:41], v[96:97]
	v_pk_mul_f32 v[36:37], v[36:37], v[100:101]
	v_pk_mul_f32 v[34:35], v[34:35], v[98:99]
	v_pk_mul_f32 v[30:31], v[30:31], v[86:87]
	v_pk_mul_f32 v[26:27], v[26:27], v[90:91]
	v_pk_mul_f32 v[22:23], v[22:23], v[94:95]
	v_pk_mul_f32 v[32:33], v[32:33], v[88:89]
	v_pk_mul_f32 v[28:29], v[28:29], v[92:93]
	v_pk_mul_f32 v[24:25], v[24:25], v[96:97]
	v_pk_mul_f32 v[20:21], v[20:21], v[100:101]
	v_pk_mul_f32 v[18:19], v[18:19], v[98:99]
	v_pk_mul_f32 v[14:15], v[14:15], v[86:87]
	v_pk_mul_f32 v[10:11], v[10:11], v[90:91]
	v_pk_mul_f32 v[6:7], v[6:7], v[94:95]
	v_pk_mul_f32 v[16:17], v[16:17], v[88:89]
	v_pk_mul_f32 v[12:13], v[12:13], v[92:93]
	v_pk_mul_f32 v[8:9], v[8:9], v[96:97]
	v_pk_mul_f32 v[4:5], v[4:5], v[100:101]
	v_pk_mul_f32 v[2:3], v[2:3], v[98:99]
.LBB0_468:
	v_add_u32_e32 v210, s2, v249
	ds_read_b64_tr_b16 v[190:191], v210 offset:24576
	ds_read_b64_tr_b16 v[192:193], v210 offset:25088
	s_waitcnt lgkmcnt(9)
	v_mfma_f32_32x32x16_bf16 v[98:113], v[82:85], v[174:177], v[66:81]
	v_add_f32_e32 v86, v130, v131
	v_add_f32_e32 v86, v132, v86
	v_add_f32_e32 v86, v133, v86
	v_add_f32_e32 v86, v134, v86
	v_add_f32_e32 v86, v135, v86
	v_cvt_pk_bf16_f32 v158, v130, v131
	v_cvt_pk_bf16_f32 v159, v132, v133
	ds_read_b64_tr_b16 v[130:131], v210 offset:28672
	ds_read_b64_tr_b16 v[132:133], v210 offset:29184
	v_add_f32_e32 v82, v136, v86
	v_add_f32_e32 v82, v137, v82
	v_add_f32_e32 v82, v138, v82
	v_add_f32_e32 v146, v139, v82
	s_waitcnt lgkmcnt(10)
	v_mfma_f32_32x32x16_bf16 v[82:97], v[202:205], v[174:177], v[66:81]
	v_cvt_pk_bf16_f32 v160, v134, v135
	v_cvt_pk_bf16_f32 v161, v136, v137
	ds_read_b64_tr_b16 v[134:135], v210 offset:25600
	ds_read_b64_tr_b16 v[136:137], v210 offset:26112
	s_waitcnt lgkmcnt(11)
	v_mfma_f32_32x32x16_bf16 v[98:113], v[206:209], v[162:165], v[98:113]
	v_add_f32_e32 v146, v140, v146
	v_add_f32_e32 v146, v141, v146
	v_add_f32_e32 v146, v142, v146
	v_add_f32_e32 v146, v143, v146
	v_cvt_pk_bf16_f32 v154, v138, v139
	v_cvt_pk_bf16_f32 v155, v140, v141
	ds_read_b64_tr_b16 v[138:139], v210 offset:29696
	ds_read_b64_tr_b16 v[140:141], v210 offset:30208
	s_waitcnt lgkmcnt(12)
	v_mfma_f32_32x32x16_bf16 v[82:97], v[198:201], v[162:165], v[82:97]
	v_add_f32_e32 v146, v144, v146
	v_add_f32_e32 v146, v145, v146
	v_add_f32_e32 v146, v114, v146
	v_add_f32_e32 v146, v115, v146
	v_cvt_pk_bf16_f32 v156, v142, v143
	v_cvt_pk_bf16_f32 v157, v144, v145
	ds_read_b64_tr_b16 v[142:143], v210 offset:26624
	ds_read_b64_tr_b16 v[144:145], v210 offset:27136
	s_waitcnt lgkmcnt(13)
	v_mfma_f32_32x32x16_bf16 v[98:113], v[194:197], v[170:173], v[98:113]
	v_add_f32_e32 v146, v116, v146
	v_add_f32_e32 v146, v117, v146
	v_add_f32_e32 v146, v118, v146
	v_add_f32_e32 v146, v119, v146
	v_cvt_pk_bf16_f32 v150, v114, v115
	v_cvt_pk_bf16_f32 v151, v116, v117
	ds_read_b64_tr_b16 v[114:115], v210 offset:30720
	ds_read_b64_tr_b16 v[116:117], v210 offset:31232
	s_waitcnt lgkmcnt(14)
	v_mfma_f32_32x32x16_bf16 v[82:97], v[186:189], v[170:173], v[82:97]
	v_add_f32_e32 v146, v120, v146
	v_add_f32_e32 v146, v121, v146
	v_add_f32_e32 v146, v122, v146
	v_add_f32_e32 v146, v123, v146
	v_cvt_pk_bf16_f32 v152, v118, v119
	v_cvt_pk_bf16_f32 v153, v120, v121
	ds_read_b64_tr_b16 v[118:119], v210 offset:27648
	ds_read_b64_tr_b16 v[120:121], v210 offset:28160
	s_waitcnt lgkmcnt(14)
	v_mfma_f32_32x32x16_bf16 v[98:113], v[182:185], v[166:169], v[98:113]
	v_add_f32_e32 v146, v124, v146
	v_add_f32_e32 v146, v125, v146
	v_add_f32_e32 v146, v126, v146
	v_add_f32_e32 v182, v127, v146
	v_cvt_pk_bf16_f32 v146, v122, v123
	v_cvt_pk_bf16_f32 v147, v124, v125
	ds_read_b64_tr_b16 v[122:123], v210 offset:31744
	ds_read_b64_tr_b16 v[124:125], v210 offset:32256
	v_mfma_f32_32x32x16_bf16 v[82:97], v[178:181], v[166:169], v[82:97]
	v_add_f32_e32 v148, v128, v182
	v_add_f32_e32 v178, v129, v148
	v_cvt_pk_bf16_f32 v148, v126, v127
	v_cvt_pk_bf16_f32 v149, v128, v129
	s_add_i32 s2, s36, s47
	s_mov_b32 m0, s2
	s_nop 0
	global_load_lds_dwordx4 v235, s[98:99]
	s_lshl_b32 s2, s14, 1
	s_add_i32 s2, s2, s64
	s_mov_b32 m0, s2
	s_nop 0
	global_load_lds_dwordx4 v237, s[98:99]
	s_addk_i32 s2, 0x2000
	s_mov_b32 m0, s2
	s_nop 0
	global_load_lds_dwordx4 v239, s[98:99]
	v_max_f32_e32 v126, v98, v99
	v_max3_f32 v127, v100, v101, v83
	v_max3_f32 v126, v126, v82, v84
	v_max3_f32 v126, v126, v85, v102
	v_max3_f32 v127, v127, v104, v105
	v_max3_f32 v126, v126, v103, v86
	v_max3_f32 v127, v127, v88, v89
	v_max3_f32 v126, v126, v87, v106
	v_max3_f32 v127, v127, v108, v109
	v_max3_f32 v126, v126, v107, v90
	v_max3_f32 v127, v127, v92, v93
	v_max3_f32 v126, v126, v91, v110
	v_max3_f32 v127, v127, v112, v113
	v_max3_f32 v126, v126, v111, v94
	v_max3_f32 v127, v127, v96, v97
	v_add_f32_e32 v215, v1, v178
	v_max3_f32 v1, v126, v95, v127
	v_cmp_lt_f32_e32 vcc, s19, v1
	s_cmp_lg_u64 vcc, 0
	s_cselect_b64 s[92:93], -1, 0
	s_cbranch_vccnz .LBB0_476

;   #define WAIT_KV() do{ if constexpr(DV==128){WAIT_BAR(3);} else {WAIT_BAR(2);} }while(0)
;   #define RESC() do{ if(resc){ asm volatile("s_waitcnt lgkmcnt(0)":::"memory"); \
;       _Pragma("unroll") for(int d_=0;d_<DV/32;++d_) _Pragma("unroll") for(int r=0;r<16;++r)o[d_][r]*=wsf[crow(r,hi)]; } }while(0)
;   #define ROT() do{sl_prev=sl_cur;sl_cur=sl_next;sl_next=(sl_next==(NSLOT-1)*SLOTB)?0:sl_next+SLOTB;}while(0)
; template<int THRL,bool WIN,int DM,int ODM,int DV,int QMODE> __device__ __forceinline__ void attn_unit(const bf16*Qp,const bf16*__restrict__ Kp,const bf16*__restrict__ Vp,bf16*Op,const int q0,const int t_lo,const int NT,const float sink2,char*shm,const float*qgain,const float*qtab,const int b0,const ...
;     ...
;   int t=1;
;   for(;t+5<NT;t+=2){
;     STEP(pB0,pB1,pA0,pA1,t,true,true,true);     WAIT_KV(); RESC(); ROT();
;     STEP(pA0,pA1,pB0,pB1,t+1,true,true,true);   WAIT_KV(); RESC(); ROT();
;   }
.LBB0_471:
	s_add_i32 s13, s13, 2
	s_add_i32 s2, s14, 0x2000
	s_cmpk_lg_i32 s14, 0x4000
	s_cselect_b32 s2, s2, 0
	s_add_u32 s6, s6, 0x90000
	s_addc_u32 s7, s7, 0
	s_add_u32 s98, s98, 0x90000
	s_addc_u32 s99, s99, 0
	s_add_i32 s3, s96, 2
	s_cmp_ge_u32 s13, s24
	s_cbranch_scc1 .Lmy_b_exitbar
	s_mov_b32 s96, s3
	s_mov_b32 s15, s36
	s_mov_b32 s3, s14
	s_mov_b32 s36, s2
	s_waitcnt vmcnt(3) lgkmcnt(0)
	s_barrier
	s_andn2_b64 vcc, exec, s[92:93]
	s_cbranch_vccnz .LBB0_465
	s_waitcnt lgkmcnt(0)
	v_add_u32_e32 v1, s65, v243
	ds_read_b128 v[114:117], v1 offset:96
	ds_read_b128 v[118:121], v1 offset:64
	ds_read_b128 v[122:125], v1 offset:32
	ds_read_b128 v[126:129], v1
	s_waitcnt lgkmcnt(3)
	v_pk_mul_f32 v[62:63], v[62:63], v[114:115]
	s_waitcnt lgkmcnt(2)
	v_pk_mul_f32 v[58:59], v[58:59], v[118:119]
	s_waitcnt lgkmcnt(1)
	v_pk_mul_f32 v[54:55], v[54:55], v[122:123]
	v_pk_mul_f32 v[64:65], v[64:65], v[116:117]
	v_pk_mul_f32 v[60:61], v[60:61], v[120:121]
	v_pk_mul_f32 v[56:57], v[56:57], v[124:125]
	s_waitcnt lgkmcnt(0)
	v_pk_mul_f32 v[52:53], v[52:53], v[128:129]
	v_pk_mul_f32 v[50:51], v[50:51], v[126:127]
	v_pk_mul_f32 v[46:47], v[46:47], v[114:115]
	v_pk_mul_f32 v[42:43], v[42:43], v[118:119]
	v_pk_mul_f32 v[38:39], v[38:39], v[122:123]
	v_pk_mul_f32 v[48:49], v[48:49], v[116:117]
	v_pk_mul_f32 v[44:45], v[44:45], v[120:121]
	v_pk_mul_f32 v[40:41], v[40:41], v[124:125]
	v_pk_mul_f32 v[36:37], v[36:37], v[128:129]
	v_pk_mul_f32 v[34:35], v[34:35], v[126:127]
	v_pk_mul_f32 v[30:31], v[30:31], v[114:115]
	v_pk_mul_f32 v[26:27], v[26:27], v[118:119]
	v_pk_mul_f32 v[22:23], v[22:23], v[122:123]
	v_pk_mul_f32 v[32:33], v[32:33], v[116:117]
	v_pk_mul_f32 v[28:29], v[28:29], v[120:121]
	v_pk_mul_f32 v[24:25], v[24:25], v[124:125]
	v_pk_mul_f32 v[20:21], v[20:21], v[128:129]
	v_pk_mul_f32 v[18:19], v[18:19], v[126:127]
	v_pk_mul_f32 v[14:15], v[14:15], v[114:115]
	v_pk_mul_f32 v[10:11], v[10:11], v[118:119]
	v_pk_mul_f32 v[6:7], v[6:7], v[122:123]
	v_pk_mul_f32 v[16:17], v[16:17], v[116:117]
	v_pk_mul_f32 v[12:13], v[12:13], v[120:121]
	v_pk_mul_f32 v[8:9], v[8:9], v[124:125]
	v_pk_mul_f32 v[4:5], v[4:5], v[128:129]
	v_pk_mul_f32 v[2:3], v[2:3], v[126:127]
	s_branch .LBB0_465
.Lmy_b_exitbar:
	s_waitcnt vmcnt(3) lgkmcnt(0)
	s_barrier
	s_andn2_b64 vcc, exec, s[92:93]
	s_cbranch_vccnz .Lmy_b_exit
	s_waitcnt lgkmcnt(0)
	v_add_u32_e32 v1, s65, v243
	ds_read_b128 v[114:117], v1 offset:96
	ds_read_b128 v[118:121], v1 offset:64
	ds_read_b128 v[122:125], v1 offset:32
	ds_read_b128 v[126:129], v1
	s_waitcnt lgkmcnt(3)
	v_pk_mul_f32 v[62:63], v[62:63], v[114:115]
	s_waitcnt lgkmcnt(2)
	v_pk_mul_f32 v[58:59], v[58:59], v[118:119]
	s_waitcnt lgkmcnt(1)
	v_pk_mul_f32 v[54:55], v[54:55], v[122:123]
	v_pk_mul_f32 v[64:65], v[64:65], v[116:117]
	v_pk_mul_f32 v[60:61], v[60:61], v[120:121]
	v_pk_mul_f32 v[56:57], v[56:57], v[124:125]
	s_waitcnt lgkmcnt(0)
	v_pk_mul_f32 v[52:53], v[52:53], v[128:129]
	v_pk_mul_f32 v[50:51], v[50:51], v[126:127]
	v_pk_mul_f32 v[46:47], v[46:47], v[114:115]
	v_pk_mul_f32 v[42:43], v[42:43], v[118:119]
	v_pk_mul_f32 v[38:39], v[38:39], v[122:123]
	v_pk_mul_f32 v[48:49], v[48:49], v[116:117]
	v_pk_mul_f32 v[44:45], v[44:45], v[120:121]
	v_pk_mul_f32 v[40:41], v[40:41], v[124:125]
	v_pk_mul_f32 v[36:37], v[36:37], v[128:129]
	v_pk_mul_f32 v[34:35], v[34:35], v[126:127]
	v_pk_mul_f32 v[30:31], v[30:31], v[114:115]
	v_pk_mul_f32 v[26:27], v[26:27], v[118:119]
	v_pk_mul_f32 v[22:23], v[22:23], v[122:123]
	v_pk_mul_f32 v[32:33], v[32:33], v[116:117]
	v_pk_mul_f32 v[28:29], v[28:29], v[120:121]
	v_pk_mul_f32 v[24:25], v[24:25], v[124:125]
	v_pk_mul_f32 v[20:21], v[20:21], v[128:129]
	v_pk_mul_f32 v[18:19], v[18:19], v[126:127]
	v_pk_mul_f32 v[14:15], v[14:15], v[114:115]
	v_pk_mul_f32 v[10:11], v[10:11], v[118:119]
	v_pk_mul_f32 v[6:7], v[6:7], v[122:123]
	v_pk_mul_f32 v[16:17], v[16:17], v[116:117]
	v_pk_mul_f32 v[12:13], v[12:13], v[120:121]
	v_pk_mul_f32 v[8:9], v[8:9], v[124:125]
	v_pk_mul_f32 v[4:5], v[4:5], v[128:129]
	v_pk_mul_f32 v[2:3], v[2:3], v[126:127]
